# selected-block attention: each workgroup works through 64-token blocks (8 consecutive tokens per wave) and stages that block's two always-selected neighbour blocks (cur-1, cur) in LDS next to block 0
# speedup vs baseline: 1.0099x; 1.0099x over previous
.LBB0_841:
	s_andn2_b64 vcc, exec, s[0:1]
	v_readlane_b32 s3, v254, 47
	s_cbranch_vccnz .LBB0_934
	s_mov_b64 s[22:23], exec
	s_and_b32 s2, s3, 1
	s_lshr_b32 s0, s3, 1
	s_and_b32 s0, s0, 3
	s_lshl_b32 s26, s0, 6
	s_lshr_b32 s0, s3, 3
	s_add_i32 s26, s26, s0
	s_mov_b32 s61, s26
	s_lshl_b32 s26, s26, 6
	v_readfirstlane_b32 s1, v220
	s_lshl_b32 s0, s1, 3
	s_add_i32 s26, s26, s0
	s_mov_b32 s60, 0
	s_lshl_b32 s0, s2, 6
	s_add_u32 s12, s12, s0
	s_addc_u32 s13, s13, 0
	s_lshl_b32 s0, s2, 21
	s_add_u32 s18, s18, s0
	s_addc_u32 s19, s19, 0
	s_add_u32 s16, s16, s0
	s_addc_u32 s17, s17, 0
	v_lshl_or_b32 v202, s2, 3, v200
	v_and_b32_e32 v140, 63, v208
	v_lshlrev_b32_e32 v140, 4, v140
	v_add_u32_e32 v141, 0x1000, v140
	s_mov_b32 s48, 0x3e38aa3b
	s_mov_b32 s49, 0x3e38aa3b
	s_mov_b32 s57, 0x20400
	v_mov_b32_e32 v179, 0xf149f2ca
	v_lshl_add_u32 v66, v202, 2, s57
	ds_read_b32 v178, v66 offset:1984
	s_barrier
	s_and_b32 s0, s1, 3
	s_lshl_b32 s0, s0, 11
	s_cmp_lt_u32 s1, 4
	s_cselect_b32 s40, s18, s16
	s_cselect_b32 s41, s19, s17
	s_cselect_b32 s2, 0, 0x2000
	s_add_u32 s40, s40, s0
	s_addc_u32 s41, s41, 0
	s_add_i32 s2, s2, s0
	s_mov_b32 m0, s2
	s_nop 0
	global_load_lds_dwordx4 v140, s[40:41]
	s_add_u32 s40, s40, 0x400
	s_addc_u32 s41, s41, 0
	s_add_i32 m0, s2, 0x400
	s_nop 0
	global_load_lds_dwordx4 v140, s[40:41]
	s_waitcnt lgkmcnt(0)
	s_barrier
	s_and_b32 s0, s1, 3
	s_lshl_b32 s0, s0, 12
	s_cmp_lt_u32 s1, 4
	s_cselect_b32 s40, s18, s16
	s_cselect_b32 s41, s19, s17
	s_cselect_b32 s2, 1, 2
	s_lshl_b32 s2, s2, 14
	s_add_i32 s2, s2, s0
	s_add_i32 s62, s61, -1
	s_lshl_b32 s62, s62, 13
	s_add_i32 s0, s0, s62
	s_ashr_i32 s62, s0, 31
	s_add_u32 s40, s40, s0
	s_addc_u32 s41, s41, s62
	s_add_i32 m0, s2, 0
	s_nop 0
	global_load_lds_dwordx4 v140, s[40:41]
	s_add_i32 m0, s2, 1024
	s_add_u32 s40, s40, 0x400
	s_addc_u32 s41, s41, 0
	global_load_lds_dwordx4 v140, s[40:41]
	s_add_i32 m0, s2, 2048
	s_add_u32 s40, s40, 0x400
	s_addc_u32 s41, s41, 0
	global_load_lds_dwordx4 v140, s[40:41]
	s_add_i32 m0, s2, 3072
	s_add_u32 s40, s40, 0x400
	s_addc_u32 s41, s41, 0
	global_load_lds_dwordx4 v140, s[40:41]
	s_waitcnt vmcnt(0)
	s_barrier
	s_lshl_b32 s0, s26, 7
	s_add_u32 s38, s12, s0
	s_addc_u32 s39, s13, 0
	v_lshrrev_b32_e32 v144, 3, v199
	global_load_dword v176, v144, s[38:39]
	s_lshl_b32 s0, s26, 11
	s_add_u32 s54, s14, s0
	s_addc_u32 s55, s15, 0
	v_lshlrev_b32_e32 v67, 7, v202
	v_lshl_add_u32 v67, v198, 1, v67
	global_load_dwordx4 v[16:19], v67, s[54:55]
	global_load_dwordx4 v[20:23], v67, s[54:55] offset:64
	s_mov_b64 s[34:35], s[18:19]
	s_mov_b64 s[36:37], s[16:17]
	ds_read_b128 v[32:35], v140 offset:0
	ds_read_b128 v[36:39], v140 offset:1024
	ds_read_b128 v[40:43], v140 offset:2048
	ds_read_b128 v[44:47], v140 offset:3072
	ds_read_b128 v[48:51], v140 offset:4096
	ds_read_b128 v[52:55], v140 offset:5120
	ds_read_b128 v[56:59], v140 offset:6144
	ds_read_b128 v[60:63], v140 offset:7168
	ds_read_b128 v[100:103], v140 offset:8192
	ds_read_b128 v[104:107], v140 offset:9216
	ds_read_b128 v[108:111], v140 offset:10240
	ds_read_b128 v[112:115], v140 offset:11264
	ds_read_b128 v[116:119], v140 offset:12288
	ds_read_b128 v[120:123], v140 offset:13312
	ds_read_b128 v[124:127], v140 offset:14336
	ds_read_b128 v[128:131], v140 offset:15360
	s_lshr_b32 s0, s26, 6
	s_add_i32 s0, s0, 1
	s_min_i32 s28, s0, 16
	s_mov_b32 s29, 0
	s_mov_b32 s30, 0
	s_mov_b32 s51, 0
	v_mov_b32_e32 v196, 0xf149f2ca
	v_mov_b32_e32 v197, 0
	v_mov_b32_e32 v0, 0
	v_mov_b32_e32 v1, 0
	v_mov_b32_e32 v2, 0
	v_mov_b32_e32 v3, 0
	v_mov_b32_e32 v4, 0
	v_mov_b32_e32 v5, 0
	v_mov_b32_e32 v6, 0
	v_mov_b32_e32 v7, 0
	v_mov_b32_e32 v8, 0
	v_mov_b32_e32 v9, 0
	v_mov_b32_e32 v10, 0
	v_mov_b32_e32 v11, 0
	v_mov_b32_e32 v12, 0
	v_mov_b32_e32 v13, 0
	v_mov_b32_e32 v14, 0
	v_mov_b32_e32 v15, 0
	s_waitcnt lgkmcnt(0)
	v_mul_f32_e32 v178, 0x3fb8aa3b, v178
	s_waitcnt vmcnt(2)
.Lsel_stepA:
	s_add_i32 s1, s29, 1
	s_cmp_ge_i32 s1, s28
	s_cbranch_scc1 .Lsel_issue_lastA
	s_mov_b32 s50, 0
	s_nop 0
	v_readlane_b32 s0, v176, s1
	s_cmp_eq_u32 s0, s61
	s_cbranch_scc1 .Lsel_ldsCA
	s_add_i32 s2, s0, 1
	s_cmp_eq_u32 s2, s61
	s_cbranch_scc1 .Lsel_ldsPA
	s_lshl_b32 s31, s0, 6
	s_lshl_b32 s0, s0, 13
	s_add_u32 s34, s18, s0
	s_addc_u32 s35, s19, 0
	s_add_u32 s36, s16, s0
	s_addc_u32 s37, s17, 0
	global_load_dwordx4 v[68:71], v140, s[34:35] offset:0
	global_load_dwordx4 v[72:75], v140, s[34:35] offset:1024
	global_load_dwordx4 v[76:79], v140, s[34:35] offset:2048
	global_load_dwordx4 v[80:83], v140, s[34:35] offset:3072
	global_load_dwordx4 v[84:87], v141, s[34:35] offset:0
	global_load_dwordx4 v[88:91], v141, s[34:35] offset:1024
	global_load_dwordx4 v[92:95], v141, s[34:35] offset:2048
	global_load_dwordx4 v[96:99], v141, s[34:35] offset:3072
	global_load_dwordx4 v[132:135], v140, s[36:37] offset:0
	global_load_dwordx4 v[136:139], v140, s[36:37] offset:1024
	global_load_dwordx4 v[148:151], v140, s[36:37] offset:2048
	global_load_dwordx4 v[152:155], v140, s[36:37] offset:3072
	global_load_dwordx4 v[156:159], v141, s[36:37] offset:0
	global_load_dwordx4 v[160:163], v141, s[36:37] offset:1024
	global_load_dwordx4 v[164:167], v141, s[36:37] offset:2048
	global_load_dwordx4 v[168:171], v141, s[36:37] offset:3072
	s_waitcnt vmcnt(16) lgkmcnt(0)
	s_branch .Lsel_computeA
.Lsel_ldsCA:
	s_lshl_b32 s31, s0, 6
	ds_read_b128 v[68:71], v140 offset:24576
	ds_read_b128 v[72:75], v140 offset:25600
	ds_read_b128 v[76:79], v140 offset:26624
	ds_read_b128 v[80:83], v140 offset:27648
	ds_read_b128 v[84:87], v140 offset:28672
	ds_read_b128 v[88:91], v140 offset:29696
	ds_read_b128 v[92:95], v140 offset:30720
	ds_read_b128 v[96:99], v140 offset:31744
	ds_read_b128 v[132:135], v140 offset:40960
	ds_read_b128 v[136:139], v140 offset:41984
	ds_read_b128 v[148:151], v140 offset:43008
	ds_read_b128 v[152:155], v140 offset:44032
	ds_read_b128 v[156:159], v140 offset:45056
	ds_read_b128 v[160:163], v140 offset:46080
	ds_read_b128 v[164:167], v140 offset:47104
	ds_read_b128 v[168:171], v140 offset:48128
	s_waitcnt vmcnt(0) lgkmcnt(0)
	s_branch .Lsel_computeA
.Lsel_ldsPA:
	s_lshl_b32 s31, s0, 6
	ds_read_b128 v[68:71], v140 offset:16384
	ds_read_b128 v[72:75], v140 offset:17408
	ds_read_b128 v[76:79], v140 offset:18432
	ds_read_b128 v[80:83], v140 offset:19456
	ds_read_b128 v[84:87], v140 offset:20480
	ds_read_b128 v[88:91], v140 offset:21504
	ds_read_b128 v[92:95], v140 offset:22528
	ds_read_b128 v[96:99], v140 offset:23552
	ds_read_b128 v[132:135], v140 offset:32768
	ds_read_b128 v[136:139], v140 offset:33792
	ds_read_b128 v[148:151], v140 offset:34816
	ds_read_b128 v[152:155], v140 offset:35840
	ds_read_b128 v[156:159], v140 offset:36864
	ds_read_b128 v[160:163], v140 offset:37888
	ds_read_b128 v[164:167], v140 offset:38912
	ds_read_b128 v[168:171], v140 offset:39936
	s_waitcnt vmcnt(0) lgkmcnt(0)
	s_branch .Lsel_computeA
.Lsel_issue_lastA:
	s_mov_b32 s50, 1
	s_lshl_b32 s0, s26, 7
	s_add_u32 s40, s20, s0
	s_addc_u32 s41, s21, 0
	v_mul_u32_u24_e32 v66, 6, v202
	global_load_ushort v64, v66, s[40:41]
	s_mul_i32 s0, s26, 0x1800
	s_add_i32 s0, s0, 0x1000
	s_add_u32 s40, s24, s0
	s_addc_u32 s41, s25, 0
	v_lshlrev_b32_e32 v67, 7, v202
	v_lshl_add_u32 v67, v182, 1, v67
	global_load_dwordx2 v[24:25], v67, s[40:41] offset:0
	global_load_dwordx2 v[26:27], v67, s[40:41] offset:32
	global_load_dwordx2 v[28:29], v67, s[40:41] offset:64
	global_load_dwordx2 v[30:31], v67, s[40:41] offset:96
	s_and_b32 s0, s60, 7
	s_cmp_eq_u32 s0, 7
	s_cselect_b32 s0, 0x7f9, 1
	s_add_i32 s56, s26, s0
	s_cmp_eq_u32 s60, 15
	s_cselect_b32 s56, s26, s56
	s_lshl_b32 s0, s56, 7
	s_add_u32 s38, s12, s0
	s_addc_u32 s39, s13, 0
	s_lshl_b32 s0, s56, 11
	s_add_u32 s54, s14, s0
	s_addc_u32 s55, s15, 0
	v_lshrrev_b32_e32 v144, 3, v199
	global_load_dword v176, v144, s[38:39]
	s_mov_b32 s31, 0
	s_mov_b64 s[34:35], s[18:19]
	s_mov_b64 s[36:37], s[16:17]
	ds_read_b128 v[68:71], v140 offset:0
	ds_read_b128 v[72:75], v140 offset:1024
	ds_read_b128 v[76:79], v140 offset:2048
	ds_read_b128 v[80:83], v140 offset:3072
	ds_read_b128 v[84:87], v140 offset:4096
	ds_read_b128 v[88:91], v140 offset:5120
	ds_read_b128 v[92:95], v140 offset:6144
	ds_read_b128 v[96:99], v140 offset:7168
	ds_read_b128 v[132:135], v140 offset:8192
	ds_read_b128 v[136:139], v140 offset:9216
	ds_read_b128 v[148:151], v140 offset:10240
	ds_read_b128 v[152:155], v140 offset:11264
	ds_read_b128 v[156:159], v140 offset:12288
	ds_read_b128 v[160:163], v140 offset:13312
	ds_read_b128 v[164:167], v140 offset:14336
	ds_read_b128 v[168:171], v140 offset:15360
	s_waitcnt vmcnt(6)

.Lsel_stepB:
	s_add_i32 s1, s29, 1
	s_cmp_ge_i32 s1, s28
	s_cbranch_scc1 .Lsel_issue_lastB
	s_mov_b32 s50, 0
	s_nop 0
	v_readlane_b32 s0, v176, s1
	s_cmp_eq_u32 s0, s61
	s_cbranch_scc1 .Lsel_ldsCB
	s_add_i32 s2, s0, 1
	s_cmp_eq_u32 s2, s61
	s_cbranch_scc1 .Lsel_ldsPB
	s_lshl_b32 s31, s0, 6
	s_lshl_b32 s0, s0, 13
	s_add_u32 s34, s18, s0
	s_addc_u32 s35, s19, 0
	s_add_u32 s36, s16, s0
	s_addc_u32 s37, s17, 0
	global_load_dwordx4 v[32:35], v140, s[34:35] offset:0
	global_load_dwordx4 v[36:39], v140, s[34:35] offset:1024
	global_load_dwordx4 v[40:43], v140, s[34:35] offset:2048
	global_load_dwordx4 v[44:47], v140, s[34:35] offset:3072
	global_load_dwordx4 v[48:51], v141, s[34:35] offset:0
	global_load_dwordx4 v[52:55], v141, s[34:35] offset:1024
	global_load_dwordx4 v[56:59], v141, s[34:35] offset:2048
	global_load_dwordx4 v[60:63], v141, s[34:35] offset:3072
	global_load_dwordx4 v[100:103], v140, s[36:37] offset:0
	global_load_dwordx4 v[104:107], v140, s[36:37] offset:1024
	global_load_dwordx4 v[108:111], v140, s[36:37] offset:2048
	global_load_dwordx4 v[112:115], v140, s[36:37] offset:3072
	global_load_dwordx4 v[116:119], v141, s[36:37] offset:0
	global_load_dwordx4 v[120:123], v141, s[36:37] offset:1024
	global_load_dwordx4 v[124:127], v141, s[36:37] offset:2048
	global_load_dwordx4 v[128:131], v141, s[36:37] offset:3072
	s_waitcnt vmcnt(16) lgkmcnt(0)
	s_branch .Lsel_computeB
.Lsel_ldsCB:
	s_lshl_b32 s31, s0, 6
	ds_read_b128 v[32:35], v140 offset:24576
	ds_read_b128 v[36:39], v140 offset:25600
	ds_read_b128 v[40:43], v140 offset:26624
	ds_read_b128 v[44:47], v140 offset:27648
	ds_read_b128 v[48:51], v140 offset:28672
	ds_read_b128 v[52:55], v140 offset:29696
	ds_read_b128 v[56:59], v140 offset:30720
	ds_read_b128 v[60:63], v140 offset:31744
	ds_read_b128 v[100:103], v140 offset:40960
	ds_read_b128 v[104:107], v140 offset:41984
	ds_read_b128 v[108:111], v140 offset:43008
	ds_read_b128 v[112:115], v140 offset:44032
	ds_read_b128 v[116:119], v140 offset:45056
	ds_read_b128 v[120:123], v140 offset:46080
	ds_read_b128 v[124:127], v140 offset:47104
	ds_read_b128 v[128:131], v140 offset:48128
	s_waitcnt vmcnt(0) lgkmcnt(0)
	s_branch .Lsel_computeB
.Lsel_ldsPB:
	s_lshl_b32 s31, s0, 6
	ds_read_b128 v[32:35], v140 offset:16384
	ds_read_b128 v[36:39], v140 offset:17408
	ds_read_b128 v[40:43], v140 offset:18432
	ds_read_b128 v[44:47], v140 offset:19456
	ds_read_b128 v[48:51], v140 offset:20480
	ds_read_b128 v[52:55], v140 offset:21504
	ds_read_b128 v[56:59], v140 offset:22528
	ds_read_b128 v[60:63], v140 offset:23552
	ds_read_b128 v[100:103], v140 offset:32768
	ds_read_b128 v[104:107], v140 offset:33792
	ds_read_b128 v[108:111], v140 offset:34816
	ds_read_b128 v[112:115], v140 offset:35840
	ds_read_b128 v[116:119], v140 offset:36864
	ds_read_b128 v[120:123], v140 offset:37888
	ds_read_b128 v[124:127], v140 offset:38912
	ds_read_b128 v[128:131], v140 offset:39936
	s_waitcnt vmcnt(0) lgkmcnt(0)
	s_branch .Lsel_computeB
.Lsel_issue_lastB:
	s_mov_b32 s50, 1
	s_lshl_b32 s0, s26, 7
	s_add_u32 s40, s20, s0
	s_addc_u32 s41, s21, 0
	v_mul_u32_u24_e32 v66, 6, v202
	global_load_ushort v64, v66, s[40:41]
	s_mul_i32 s0, s26, 0x1800
	s_add_i32 s0, s0, 0x1000
	s_add_u32 s40, s24, s0
	s_addc_u32 s41, s25, 0
	v_lshlrev_b32_e32 v67, 7, v202
	v_lshl_add_u32 v67, v182, 1, v67
	global_load_dwordx2 v[24:25], v67, s[40:41] offset:0
	global_load_dwordx2 v[26:27], v67, s[40:41] offset:32
	global_load_dwordx2 v[28:29], v67, s[40:41] offset:64
	global_load_dwordx2 v[30:31], v67, s[40:41] offset:96
	s_and_b32 s0, s60, 7
	s_cmp_eq_u32 s0, 7
	s_cselect_b32 s0, 0x7f9, 1
	s_add_i32 s56, s26, s0
	s_cmp_eq_u32 s60, 15
	s_cselect_b32 s56, s26, s56
	s_lshl_b32 s0, s56, 7
	s_add_u32 s38, s12, s0
	s_addc_u32 s39, s13, 0
	s_lshl_b32 s0, s56, 11
	s_add_u32 s54, s14, s0
	s_addc_u32 s55, s15, 0
	v_lshrrev_b32_e32 v144, 3, v199
	global_load_dword v176, v144, s[38:39]
	s_mov_b32 s31, 0
	s_mov_b64 s[34:35], s[18:19]
	s_mov_b64 s[36:37], s[16:17]
	ds_read_b128 v[32:35], v140 offset:0
	ds_read_b128 v[36:39], v140 offset:1024
	ds_read_b128 v[40:43], v140 offset:2048
	ds_read_b128 v[44:47], v140 offset:3072
	ds_read_b128 v[48:51], v140 offset:4096
	ds_read_b128 v[52:55], v140 offset:5120
	ds_read_b128 v[56:59], v140 offset:6144
	ds_read_b128 v[60:63], v140 offset:7168
	ds_read_b128 v[100:103], v140 offset:8192
	ds_read_b128 v[104:107], v140 offset:9216
	ds_read_b128 v[108:111], v140 offset:10240
	ds_read_b128 v[112:115], v140 offset:11264
	ds_read_b128 v[116:119], v140 offset:12288
	ds_read_b128 v[120:123], v140 offset:13312
	ds_read_b128 v[124:127], v140 offset:14336
	ds_read_b128 v[128:131], v140 offset:15360
	s_waitcnt vmcnt(6)

.Lsel_epilogue:
	s_waitcnt vmcnt(3)
	s_nop 7
	ds_bpermute_b32 v66, v180, v197
	s_waitcnt lgkmcnt(0)
	v_add_f32_e32 v197, v197, v66
	ds_bpermute_b32 v66, v181, v197
	v_lshlrev_b32_e32 v67, 16, v64
	v_mul_f32_e32 v67, 0xbfb8aa3b, v67
	v_exp_f32_e32 v67, v67
	s_waitcnt lgkmcnt(0)
	v_add_f32_e32 v197, v197, v66
	v_add_f32_e32 v67, 1.0, v67
	v_mul_f32_e32 v67, v67, v197
	v_rcp_f32_e32 v67, v67
	s_nop 0
	v_lshlrev_b32_e32 v144, 16, v24
	v_and_b32_e32 v145, 0xffff0000, v24
	v_lshlrev_b32_e32 v143, 16, v25
	v_and_b32_e32 v177, 0xffff0000, v25
	v_fmac_f32_e32 v144, v0, v67
	v_fmac_f32_e32 v145, v1, v67
	v_fmac_f32_e32 v143, v2, v67
	v_fmac_f32_e32 v177, v3, v67
	v_cvt_pk_bf16_f32 v24, v144, v145
	v_cvt_pk_bf16_f32 v25, v143, v177
	v_lshlrev_b32_e32 v144, 16, v26
	v_and_b32_e32 v145, 0xffff0000, v26
	v_lshlrev_b32_e32 v143, 16, v27
	v_and_b32_e32 v177, 0xffff0000, v27
	v_fmac_f32_e32 v144, v4, v67
	v_fmac_f32_e32 v145, v5, v67
	v_fmac_f32_e32 v143, v6, v67
	v_fmac_f32_e32 v177, v7, v67
	v_cvt_pk_bf16_f32 v26, v144, v145
	v_cvt_pk_bf16_f32 v27, v143, v177
	v_lshlrev_b32_e32 v144, 16, v28
	v_and_b32_e32 v145, 0xffff0000, v28
	v_lshlrev_b32_e32 v143, 16, v29
	v_and_b32_e32 v177, 0xffff0000, v29
	v_fmac_f32_e32 v144, v8, v67
	v_fmac_f32_e32 v145, v9, v67
	v_fmac_f32_e32 v143, v10, v67
	v_fmac_f32_e32 v177, v11, v67
	v_cvt_pk_bf16_f32 v28, v144, v145
	v_cvt_pk_bf16_f32 v29, v143, v177
	v_lshlrev_b32_e32 v144, 16, v30
	v_and_b32_e32 v145, 0xffff0000, v30
	v_lshlrev_b32_e32 v143, 16, v31
	v_and_b32_e32 v177, 0xffff0000, v31
	v_fmac_f32_e32 v144, v12, v67
	v_fmac_f32_e32 v145, v13, v67
	v_fmac_f32_e32 v143, v14, v67
	v_fmac_f32_e32 v177, v15, v67
	v_cvt_pk_bf16_f32 v30, v144, v145
	v_cvt_pk_bf16_f32 v31, v143, v177
	v_lshlrev_b32_e32 v66, 7, v202
	v_lshl_add_u32 v66, v182, 1, v66
	s_and_saveexec_b64 s[0:1], s[8:9]
	global_store_dwordx2 v66, v[24:25], s[40:41] offset:0
	global_store_dwordx2 v66, v[26:27], s[40:41] offset:32
	global_store_dwordx2 v66, v[28:29], s[40:41] offset:64
	global_store_dwordx2 v66, v[30:31], s[40:41] offset:96
	s_mov_b64 exec, s[0:1]
	s_add_i32 s60, s60, 1
	s_cmp_ge_i32 s60, 16
	s_cbranch_scc1 .Lsel_exit
	s_mov_b32 s26, s56
	s_lshr_b32 s61, s26, 6
	s_and_b32 s0, s60, 7
	s_cmp_lg_u32 s0, 0
	s_cbranch_scc1 .Lsel_samerun
	v_readfirstlane_b32 s1, v220
	s_waitcnt lgkmcnt(0)
	s_barrier
	s_and_b32 s0, s1, 3
	s_lshl_b32 s0, s0, 12
	s_cmp_lt_u32 s1, 4
	s_cselect_b32 s40, s18, s16
	s_cselect_b32 s41, s19, s17
	s_cselect_b32 s2, 1, 2
	s_lshl_b32 s2, s2, 14
	s_add_i32 s2, s2, s0
	s_add_i32 s62, s61, -1
	s_lshl_b32 s62, s62, 13
	s_add_i32 s0, s0, s62
	s_ashr_i32 s62, s0, 31
	s_add_u32 s40, s40, s0
	s_addc_u32 s41, s41, s62
	s_add_i32 m0, s2, 0
	s_nop 0
	global_load_lds_dwordx4 v140, s[40:41]
	s_add_i32 m0, s2, 1024
	s_add_u32 s40, s40, 0x400
	s_addc_u32 s41, s41, 0
	global_load_lds_dwordx4 v140, s[40:41]
	s_add_i32 m0, s2, 2048
	s_add_u32 s40, s40, 0x400
	s_addc_u32 s41, s41, 0
	global_load_lds_dwordx4 v140, s[40:41]
	s_add_i32 m0, s2, 3072
	s_add_u32 s40, s40, 0x400
	s_addc_u32 s41, s41, 0
	global_load_lds_dwordx4 v140, s[40:41]
	s_waitcnt vmcnt(0)
	s_barrier
.Lsel_samerun:
	s_lshr_b32 s0, s26, 6
	s_add_i32 s0, s0, 1
	s_min_i32 s28, s0, 16
	s_mov_b32 s29, 0
	s_mov_b32 s30, 0
	v_mov_b32_e32 v196, 0xf149f2ca
	v_mov_b32_e32 v197, 0
	v_mov_b32_e32 v0, 0
	v_mov_b32_e32 v1, 0
	v_mov_b32_e32 v2, 0
	v_mov_b32_e32 v3, 0
	v_mov_b32_e32 v4, 0
	v_mov_b32_e32 v5, 0
	v_mov_b32_e32 v6, 0
	v_mov_b32_e32 v7, 0
	v_mov_b32_e32 v8, 0
	v_mov_b32_e32 v9, 0
	v_mov_b32_e32 v10, 0
	v_mov_b32_e32 v11, 0
	v_mov_b32_e32 v12, 0
	v_mov_b32_e32 v13, 0
	v_mov_b32_e32 v14, 0
	v_mov_b32_e32 v15, 0
	s_waitcnt vmcnt(6)
	s_cmp_eq_u32 s51, 0
	s_cbranch_scc1 .Lsel_stepB
	s_branch .Lsel_stepA
